# global barriers: 20th and 28th arrivers of each XCD issue buffer_wbl2 early (two partial flushes)
# baseline (speedup 1.0000x reference)
; __device__ __forceinline__ unsigned xb_ld(unsigned* p)              { return __hip_atomic_load(p, __ATOMIC_RELAXED, __HIP_MEMORY_SCOPE_AGENT); }
; __device__ __forceinline__ unsigned xb_add(unsigned* p, unsigned v) { return __hip_atomic_fetch_add(p, v, __ATOMIC_RELAXED, __HIP_MEMORY_SCOPE_AGENT); }
; #define XB_SPIN(cond, bar) do { unsigned _sp = 0; while (cond) { __builtin_amdgcn_s_sleep(1); \
;     if ((++_sp & 255u) == 0u) { if (xb_ld(&(bar)[XB_TMO])) break; if (_sp > XB_SPIN_CAP) { atomicAdd(&(bar)[XB_TMO], 1u); break; } } } } while (0)
; __device__ __forceinline__ void xcd_barrier(const XcdBarrier& b) {
;     ...
;     if (threadIdx.x == 0) {
;         unsigned* bar = b.bar;
;         __builtin_amdgcn_s_waitcnt(0);
;         unsigned nloc = b.st[0], nx = b.st[1];
;         if (nloc == 0u) { xcd_barrier_complete(bar, b.x, nloc, nx); b.st[0] = nloc; b.st[1] = nx; }
;         const unsigned old = xb_add(&bar[XB_XSUB(b.x)], 1u);
;         const unsigned gen = old / nloc;
;         if (old + 1u == (gen + 1u) * nloc) {
;             __builtin_amdgcn_fence(__ATOMIC_RELEASE, "agent");
;             asm volatile("s_waitcnt vmcnt(0)" ::: "memory");
;             const unsigned og = xb_add(&bar[XB_TOP], 1u);
;             const unsigned tg = og / nx;
;             if (og + 1u == (tg + 1u) * nx) xb_add(&bar[XB_TOPGEN], 1u);
;             else XB_SPIN(xb_ld(&bar[XB_TOPGEN]) == tg, bar);
;             __builtin_amdgcn_fence(__ATOMIC_ACQUIRE, "agent");
;             xb_add(&bar[XB_XGEN(b.x)], 1u);
;             asm volatile("s_waitcnt vmcnt(0)" ::: "memory");
.Lgbar_mid_0:
	v_add_u32_e32 v3, 4, v3
	v_cmp_eq_u32_e32 vcc, v3, v5
	s_cbranch_vccnz .Lgbar_fl_0
	v_add_u32_e32 v3, 8, v3
	v_cmp_ne_u32_e32 vcc, v3, v5
	s_cbranch_vccnz .Lgbar_poll_0
.Lgbar_fl_0:
	buffer_wbl2 sc1
	s_waitcnt vmcnt(0)
